# ssd M-build: a_cum/dt LDS reads issued per 4-element group ahead of the masked exp chains, per-element branches removed
# speedup vs baseline: 1.0020x; 1.0020x over previous
.LBB0_535:
	s_or_b32 s34, s20, s4
	s_ashr_i32 s35, s34, 31
	s_lshl_b64 s[6:7], s[34:35], 14
	v_or_b32_e32 v24, s6, v138
	v_mov_b32_e32 v25, s7
	v_or_b32_e32 v46, 0x1000, v24
	v_mov_b32_e32 v47, s7
	v_lshl_add_u64 v[30:31], v[156:157], 0, v[24:25]
	v_lshl_add_u64 v[32:33], v[156:157], 0, v[46:47]
	v_or_b32_e32 v62, 0x2000, v24
	v_mov_b32_e32 v63, s7
	v_or_b32_e32 v24, 0x3000, v24
	v_lshl_add_u64 v[38:39], v[156:157], 0, v[62:63]
	global_load_dwordx4 v[86:89], v[32:33], off
	global_load_dwordx4 v[90:93], v[38:39], off
	v_lshl_add_u64 v[32:33], v[156:157], 0, v[24:25]
	v_lshl_add_u64 v[48:49], v[158:159], 0, v[46:47]
	global_load_dwordx4 v[94:97], v[30:31], off
	global_load_dwordx4 v[38:41], v[30:31], off offset:64
	global_load_dwordx4 v[98:101], v[32:33], off
	global_load_dwordx4 v[50:53], v[48:49], off
	v_lshl_add_u64 v[32:33], v[158:159], 0, v[62:63]
	v_lshl_add_u64 v[48:49], v[158:159], 0, v[24:25]
	s_lshl_b32 s6, s34, 6
	global_load_dwordx4 v[70:73], v[32:33], off
	global_load_dwordx4 v[74:77], v[48:49], off
	v_lshl_add_u64 v[32:33], v[160:161], 0, v[46:47]
	v_lshl_add_u64 v[48:49], v[160:161], 0, v[62:63]
	s_ashr_i32 s7, s6, 31
	global_load_dwordx4 v[54:57], v[32:33], off
	global_load_dwordx4 v[58:61], v[48:49], off
	v_lshl_add_u64 v[48:49], v[160:161], 0, v[24:25]
	v_lshl_add_u64 v[46:47], v[162:163], 0, v[46:47]
	v_lshl_add_u64 v[62:63], v[162:163], 0, v[62:63]
	v_lshl_add_u64 v[24:25], v[162:163], 0, v[24:25]
	s_lshl_b64 s[6:7], s[6:7], 1
	global_load_dwordx4 v[78:81], v[30:31], off offset:128
	s_nop 0
	global_load_dwordx4 v[30:33], v[30:31], off offset:192
	s_nop 0
	global_load_dwordx4 v[82:85], v[48:49], off
	s_nop 0
	global_load_dwordx4 v[46:49], v[46:47], off
	s_nop 0
	global_load_dwordx4 v[62:65], v[62:63], off
	s_nop 0
	global_load_dwordx4 v[66:69], v[24:25], off
	v_lshl_add_u64 v[24:25], v[164:165], 0, s[6:7]
	global_load_dwordx2 v[186:187], v[24:25], off
	global_load_dwordx2 v[184:185], v[24:25], off offset:32
	global_load_dwordx2 v[182:183], v[24:25], off offset:64
	global_load_dwordx2 v[180:181], v[24:25], off offset:96
	v_lshl_add_u64 v[24:25], v[166:167], 0, s[6:7]
	global_load_dwordx2 v[178:179], v[24:25], off
	global_load_dwordx2 v[176:177], v[24:25], off offset:32
	global_load_dwordx2 v[174:175], v[24:25], off offset:64
	global_load_dwordx2 v[172:173], v[24:25], off offset:96
	s_or_b32 s4, s4, s23
	v_mov_b32_e32 v118, v22
	v_lshl_add_u32 v22, s4, 2, v190
	v_mov_b32_e32 v119, v23
	ds_read_b32 v23, v22
	v_mov_b32_e32 v169, v117
	v_mov_b32_e32 v168, v116
	v_mov_b32_e32 v171, v155
	v_mov_b32_e32 v170, v154
	v_mov_b32_e32 v131, v45
	v_mov_b32_e32 v130, v44
	v_mov_b32_e32 v133, v105
	v_mov_b32_e32 v132, v104
	v_mov_b32_e32 v151, v113
	v_mov_b32_e32 v150, v112
	v_mov_b32_e32 v153, v115
	v_mov_b32_e32 v152, v114
	v_mov_b32_e32 v127, v37
	v_mov_b32_e32 v126, v36
	v_mov_b32_e32 v129, v43
	v_mov_b32_e32 v128, v42
	v_mov_b32_e32 v147, v109
	v_mov_b32_e32 v146, v108
	v_mov_b32_e32 v149, v111
	v_mov_b32_e32 v148, v110
	v_mov_b32_e32 v123, v29
	v_mov_b32_e32 v122, v28
	v_mov_b32_e32 v125, v35
	v_mov_b32_e32 v124, v34
	v_mov_b32_e32 v135, v103
	v_mov_b32_e32 v134, v102
	v_mov_b32_e32 v137, v107
	v_mov_b32_e32 v136, v106
	v_mov_b32_e32 v121, v27
	v_mov_b32_e32 v120, v26
	v_mov_b32_e32 v24, 0
	v_mov_b32_e32 v25, 0
	v_add_u32_e32 v108, s4, v191
	v_lshl_add_u32 v108, v108, 2, 0
	v_add_u32_e32 v109, 0x22000, v108
	ds_read_b32 v109, v109
	v_add_u32_e32 v108, 0x21800, v108
	ds_read_b32 v108, v108
	v_add_u32_e32 v110, s4, v192
	v_lshl_add_u32 v110, v110, 2, 0
	v_add_u32_e32 v111, 0x22000, v110
	ds_read_b32 v111, v111
	v_add_u32_e32 v110, 0x21800, v110
	ds_read_b32 v110, v110
	v_add_u32_e32 v112, s4, v193
	v_lshl_add_u32 v112, v112, 2, 0
	v_add_u32_e32 v113, 0x22000, v112
	ds_read_b32 v113, v113
	v_add_u32_e32 v112, 0x21800, v112
	ds_read_b32 v112, v112
	v_add_u32_e32 v114, s4, v194
	v_lshl_add_u32 v114, v114, 2, 0
	v_add_u32_e32 v115, 0x22000, v114
	ds_read_b32 v115, v115
	v_add_u32_e32 v114, 0x21800, v114
	ds_read_b32 v114, v114
	s_and_saveexec_b64 s[70:71], s[38:39]
	s_waitcnt lgkmcnt(7)
	v_sub_f32_e32 v109, v23, v109
	v_mul_f32_e32 v109, 0x3fb8aa3b, v109
	v_exp_f32_e32 v109, v109
	s_nop 0
	v_mul_f32_e32 v109, v6, v109
	s_waitcnt lgkmcnt(6)
	v_mul_f32_e32 v25, v108, v109
	s_or_b64 exec, exec, s[70:71]
	s_and_saveexec_b64 s[70:71], s[40:41]
	s_waitcnt lgkmcnt(5)
	v_sub_f32_e32 v111, v23, v111
	v_mul_f32_e32 v111, 0x3fb8aa3b, v111
	v_exp_f32_e32 v111, v111
	s_nop 0
	v_mul_f32_e32 v111, v7, v111
	s_waitcnt lgkmcnt(4)
	v_mul_f32_e32 v24, v110, v111
	s_or_b64 exec, exec, s[70:71]
	v_mov_b32_e32 v26, 0
	v_mov_b32_e32 v27, 0
	s_and_saveexec_b64 s[70:71], s[42:43]
	s_waitcnt lgkmcnt(3)
	v_sub_f32_e32 v113, v23, v113
	v_mul_f32_e32 v113, 0x3fb8aa3b, v113
	v_exp_f32_e32 v113, v113
	s_nop 0
	v_mul_f32_e32 v113, v8, v113
	s_waitcnt lgkmcnt(2)
	v_mul_f32_e32 v27, v112, v113
	s_or_b64 exec, exec, s[70:71]
	s_and_saveexec_b64 s[70:71], s[44:45]
	s_waitcnt lgkmcnt(1)
	v_sub_f32_e32 v115, v23, v115
	v_mul_f32_e32 v115, 0x3fb8aa3b, v115
	v_exp_f32_e32 v115, v115
	s_nop 0
	v_mul_f32_e32 v115, v9, v115
	s_waitcnt lgkmcnt(0)
	v_mul_f32_e32 v26, v114, v115
	s_or_b64 exec, exec, s[70:71]
	v_cvt_pk_bf16_f32 v24, v25, v24
	v_cvt_pk_bf16_f32 v25, v27, v26
	ds_write_b64 v214, v[24:25]
	v_mov_b32_e32 v24, 0
	v_mov_b32_e32 v25, 0
	v_add_u32_e32 v108, s4, v195
	v_lshl_add_u32 v108, v108, 2, 0
	v_add_u32_e32 v109, 0x22000, v108
	ds_read_b32 v109, v109
	v_add_u32_e32 v108, 0x21800, v108
	ds_read_b32 v108, v108
	v_add_u32_e32 v110, s4, v196
	v_lshl_add_u32 v110, v110, 2, 0
	v_add_u32_e32 v111, 0x22000, v110
	ds_read_b32 v111, v111
	v_add_u32_e32 v110, 0x21800, v110
	ds_read_b32 v110, v110
	v_add_u32_e32 v112, s4, v197
	v_lshl_add_u32 v112, v112, 2, 0
	v_add_u32_e32 v113, 0x22000, v112
	ds_read_b32 v113, v113
	v_add_u32_e32 v112, 0x21800, v112
	ds_read_b32 v112, v112
	v_add_u32_e32 v114, s4, v198
	v_lshl_add_u32 v114, v114, 2, 0
	v_add_u32_e32 v115, 0x22000, v114
	ds_read_b32 v115, v115
	v_add_u32_e32 v114, 0x21800, v114
	ds_read_b32 v114, v114
	s_and_saveexec_b64 s[70:71], s[46:47]
	s_waitcnt lgkmcnt(7)
	v_sub_f32_e32 v109, v23, v109
	v_mul_f32_e32 v109, 0x3fb8aa3b, v109
	v_exp_f32_e32 v109, v109
	s_nop 0
	v_mul_f32_e32 v109, v10, v109
	s_waitcnt lgkmcnt(6)
	v_mul_f32_e32 v25, v108, v109
	s_or_b64 exec, exec, s[70:71]
	s_and_saveexec_b64 s[70:71], s[48:49]
	s_waitcnt lgkmcnt(5)
	v_sub_f32_e32 v111, v23, v111
	v_mul_f32_e32 v111, 0x3fb8aa3b, v111
	v_exp_f32_e32 v111, v111
	s_nop 0
	v_mul_f32_e32 v111, v11, v111
	s_waitcnt lgkmcnt(4)
	v_mul_f32_e32 v24, v110, v111
	s_or_b64 exec, exec, s[70:71]
	v_mov_b32_e32 v26, 0
	v_mov_b32_e32 v27, 0
	s_and_saveexec_b64 s[70:71], s[50:51]
	s_waitcnt lgkmcnt(3)
	v_sub_f32_e32 v113, v23, v113
	v_mul_f32_e32 v113, 0x3fb8aa3b, v113
	v_exp_f32_e32 v113, v113
	s_nop 0
	v_mul_f32_e32 v113, v12, v113
	s_waitcnt lgkmcnt(2)
	v_mul_f32_e32 v27, v112, v113
	s_or_b64 exec, exec, s[70:71]
	s_and_saveexec_b64 s[70:71], s[52:53]
	s_waitcnt lgkmcnt(1)
	v_sub_f32_e32 v115, v23, v115
	v_mul_f32_e32 v115, 0x3fb8aa3b, v115
	v_exp_f32_e32 v115, v115
	s_nop 0
	v_mul_f32_e32 v115, v13, v115
	s_waitcnt lgkmcnt(0)
	v_mul_f32_e32 v26, v114, v115
	s_or_b64 exec, exec, s[70:71]
	v_cvt_pk_bf16_f32 v24, v25, v24
	v_cvt_pk_bf16_f32 v25, v27, v26
	ds_write_b64 v214, v[24:25] offset:32
	v_mov_b32_e32 v24, 0
	v_mov_b32_e32 v25, 0
	v_add_u32_e32 v108, s4, v199
	v_lshl_add_u32 v108, v108, 2, 0
	v_add_u32_e32 v109, 0x22000, v108
	ds_read_b32 v109, v109
	v_add_u32_e32 v108, 0x21800, v108
	ds_read_b32 v108, v108
	v_add_u32_e32 v110, s4, v200
	v_lshl_add_u32 v110, v110, 2, 0
	v_add_u32_e32 v111, 0x22000, v110
	ds_read_b32 v111, v111
	v_add_u32_e32 v110, 0x21800, v110
	ds_read_b32 v110, v110
	v_add_u32_e32 v112, s4, v201
	v_lshl_add_u32 v112, v112, 2, 0
	v_add_u32_e32 v113, 0x22000, v112
	ds_read_b32 v113, v113
	v_add_u32_e32 v112, 0x21800, v112
	ds_read_b32 v112, v112
	v_add_u32_e32 v114, s4, v202
	v_lshl_add_u32 v114, v114, 2, 0
	v_add_u32_e32 v115, 0x22000, v114
	ds_read_b32 v115, v115
	v_add_u32_e32 v114, 0x21800, v114
	ds_read_b32 v114, v114
	s_and_saveexec_b64 s[70:71], s[54:55]
	s_waitcnt lgkmcnt(7)
	v_sub_f32_e32 v109, v23, v109
	v_mul_f32_e32 v109, 0x3fb8aa3b, v109
	v_exp_f32_e32 v109, v109
	s_nop 0
	v_mul_f32_e32 v109, v14, v109
	s_waitcnt lgkmcnt(6)
	v_mul_f32_e32 v25, v108, v109
	s_or_b64 exec, exec, s[70:71]
	s_and_saveexec_b64 s[70:71], s[56:57]
	s_waitcnt lgkmcnt(5)
	v_sub_f32_e32 v111, v23, v111
	v_mul_f32_e32 v111, 0x3fb8aa3b, v111
	v_exp_f32_e32 v111, v111
	s_nop 0
	v_mul_f32_e32 v111, v15, v111
	s_waitcnt lgkmcnt(4)
	v_mul_f32_e32 v24, v110, v111
	s_or_b64 exec, exec, s[70:71]
	v_mov_b32_e32 v26, 0
	v_mov_b32_e32 v27, 0
	s_and_saveexec_b64 s[70:71], s[58:59]
	s_waitcnt lgkmcnt(3)
	v_sub_f32_e32 v113, v23, v113
	v_mul_f32_e32 v113, 0x3fb8aa3b, v113
	v_exp_f32_e32 v113, v113
	s_nop 0
	v_mul_f32_e32 v113, v16, v113
	s_waitcnt lgkmcnt(2)
	v_mul_f32_e32 v27, v112, v113
	s_or_b64 exec, exec, s[70:71]
	s_and_saveexec_b64 s[70:71], s[60:61]
	s_waitcnt lgkmcnt(1)
	v_sub_f32_e32 v115, v23, v115
	v_mul_f32_e32 v115, 0x3fb8aa3b, v115
	v_exp_f32_e32 v115, v115
	s_nop 0
	v_mul_f32_e32 v115, v17, v115
	s_waitcnt lgkmcnt(0)
	v_mul_f32_e32 v26, v114, v115
	s_or_b64 exec, exec, s[70:71]
	v_cvt_pk_bf16_f32 v24, v25, v24
	v_cvt_pk_bf16_f32 v25, v27, v26
	ds_write_b64 v214, v[24:25] offset:64
	v_mov_b32_e32 v24, 0
	v_mov_b32_e32 v25, 0
	v_add_u32_e32 v108, s4, v203
	v_lshl_add_u32 v108, v108, 2, 0
	v_add_u32_e32 v109, 0x22000, v108
	ds_read_b32 v109, v109
	v_add_u32_e32 v108, 0x21800, v108
	ds_read_b32 v108, v108
	v_add_u32_e32 v110, s4, v204
	v_lshl_add_u32 v110, v110, 2, 0
	v_add_u32_e32 v111, 0x22000, v110
	ds_read_b32 v111, v111
	v_add_u32_e32 v110, 0x21800, v110
	ds_read_b32 v110, v110
	v_add_u32_e32 v112, s4, v205
	v_lshl_add_u32 v112, v112, 2, 0
	v_add_u32_e32 v113, 0x22000, v112
	ds_read_b32 v113, v113
	v_add_u32_e32 v112, 0x21800, v112
	ds_read_b32 v112, v112
	v_add_u32_e32 v114, s4, v206
	v_lshl_add_u32 v114, v114, 2, 0
	v_add_u32_e32 v115, 0x22000, v114
	ds_read_b32 v115, v115
	v_add_u32_e32 v114, 0x21800, v114
	ds_read_b32 v114, v114
	s_and_saveexec_b64 s[70:71], s[62:63]
	s_waitcnt lgkmcnt(7)
	v_sub_f32_e32 v109, v23, v109
	v_mul_f32_e32 v109, 0x3fb8aa3b, v109
	v_exp_f32_e32 v109, v109
	s_nop 0
	v_mul_f32_e32 v109, v18, v109
	s_waitcnt lgkmcnt(6)
	v_mul_f32_e32 v25, v108, v109
	s_or_b64 exec, exec, s[70:71]
	s_and_saveexec_b64 s[70:71], s[64:65]
	s_waitcnt lgkmcnt(5)
	v_sub_f32_e32 v111, v23, v111
	v_mul_f32_e32 v111, 0x3fb8aa3b, v111
	v_exp_f32_e32 v111, v111
	s_nop 0
	v_mul_f32_e32 v111, v19, v111
	s_waitcnt lgkmcnt(4)
	v_mul_f32_e32 v24, v110, v111
	s_or_b64 exec, exec, s[70:71]
	v_mov_b32_e32 v26, 0
	v_mov_b32_e32 v27, 0
	s_and_saveexec_b64 s[70:71], s[66:67]
	s_waitcnt lgkmcnt(3)
	v_sub_f32_e32 v113, v23, v113
	v_mul_f32_e32 v113, 0x3fb8aa3b, v113
	v_exp_f32_e32 v113, v113
	s_nop 0
	v_mul_f32_e32 v113, v20, v113
	s_waitcnt lgkmcnt(2)
	v_mul_f32_e32 v27, v112, v113
	s_or_b64 exec, exec, s[70:71]
	s_and_saveexec_b64 s[70:71], s[68:69]
	s_waitcnt lgkmcnt(1)
	v_sub_f32_e32 v115, v23, v115
	v_mul_f32_e32 v115, 0x3fb8aa3b, v115
	v_exp_f32_e32 v115, v115
	s_nop 0
	v_mul_f32_e32 v115, v21, v115
	s_waitcnt lgkmcnt(0)
	v_mul_f32_e32 v26, v114, v115
	s_or_b64 exec, exec, s[70:71]
	s_waitcnt lgkmcnt(3)
	v_cvt_pk_bf16_f32 v24, v25, v24
	v_cvt_pk_bf16_f32 v25, v27, v26
	ds_write_b64 v214, v[24:25] offset:96
	ds_read_b32 v22, v22 offset:4
	s_or_b32 s4, s4, 1
	v_mov_b32_e32 v23, 0
	v_mov_b32_e32 v24, 0
	v_add_u32_e32 v108, s4, v191
	v_lshl_add_u32 v108, v108, 2, 0
	v_add_u32_e32 v109, 0x22000, v108
	ds_read_b32 v109, v109
	v_add_u32_e32 v108, 0x21800, v108
	ds_read_b32 v108, v108
	v_add_u32_e32 v110, s4, v192
	v_lshl_add_u32 v110, v110, 2, 0
	v_add_u32_e32 v111, 0x22000, v110
	ds_read_b32 v111, v111
	v_add_u32_e32 v110, 0x21800, v110
	ds_read_b32 v110, v110
	v_add_u32_e32 v112, s4, v193
	v_lshl_add_u32 v112, v112, 2, 0
	v_add_u32_e32 v113, 0x22000, v112
	ds_read_b32 v113, v113
	v_add_u32_e32 v112, 0x21800, v112
	ds_read_b32 v112, v112
	v_add_u32_e32 v114, s4, v194
	v_lshl_add_u32 v114, v114, 2, 0
	v_add_u32_e32 v115, 0x22000, v114
	ds_read_b32 v115, v115
	v_add_u32_e32 v114, 0x21800, v114
	ds_read_b32 v114, v114
	s_and_saveexec_b64 s[70:71], s[38:39]
	s_waitcnt lgkmcnt(7)
	v_sub_f32_e32 v109, v22, v109
	v_mul_f32_e32 v109, 0x3fb8aa3b, v109
	v_exp_f32_e32 v109, v109
	s_nop 0
	v_mul_f32_e32 v109, v6, v109
	s_waitcnt lgkmcnt(6)
	v_mul_f32_e32 v24, v108, v109
	s_or_b64 exec, exec, s[70:71]
	s_and_saveexec_b64 s[70:71], s[40:41]
	s_waitcnt lgkmcnt(5)
	v_sub_f32_e32 v111, v22, v111
	v_mul_f32_e32 v111, 0x3fb8aa3b, v111
	v_exp_f32_e32 v111, v111
	s_nop 0
	v_mul_f32_e32 v111, v7, v111
	s_waitcnt lgkmcnt(4)
	v_mul_f32_e32 v23, v110, v111
	s_or_b64 exec, exec, s[70:71]
	v_mov_b32_e32 v25, 0
	v_mov_b32_e32 v26, 0
	s_and_saveexec_b64 s[70:71], s[42:43]
	s_waitcnt lgkmcnt(3)
	v_sub_f32_e32 v113, v22, v113
	v_mul_f32_e32 v113, 0x3fb8aa3b, v113
	v_exp_f32_e32 v113, v113
	s_nop 0
	v_mul_f32_e32 v113, v8, v113
	s_waitcnt lgkmcnt(2)
	v_mul_f32_e32 v26, v112, v113
	s_or_b64 exec, exec, s[70:71]
	s_and_saveexec_b64 s[70:71], s[44:45]
	s_waitcnt lgkmcnt(1)
	v_sub_f32_e32 v115, v22, v115
	v_mul_f32_e32 v115, 0x3fb8aa3b, v115
	v_exp_f32_e32 v115, v115
	s_nop 0
	v_mul_f32_e32 v115, v9, v115
	s_waitcnt lgkmcnt(0)
	v_mul_f32_e32 v25, v114, v115
	s_or_b64 exec, exec, s[70:71]
	v_cvt_pk_bf16_f32 v24, v24, v23
	v_cvt_pk_bf16_f32 v25, v26, v25
	ds_write_b64 v214, v[24:25] offset:9216
	v_mov_b32_e32 v23, 0
	v_mov_b32_e32 v24, 0
	v_add_u32_e32 v108, s4, v195
	v_lshl_add_u32 v108, v108, 2, 0
	v_add_u32_e32 v109, 0x22000, v108
	ds_read_b32 v109, v109
	v_add_u32_e32 v108, 0x21800, v108
	ds_read_b32 v108, v108
	v_add_u32_e32 v110, s4, v196
	v_lshl_add_u32 v110, v110, 2, 0
	v_add_u32_e32 v111, 0x22000, v110
	ds_read_b32 v111, v111
	v_add_u32_e32 v110, 0x21800, v110
	ds_read_b32 v110, v110
	v_add_u32_e32 v112, s4, v197
	v_lshl_add_u32 v112, v112, 2, 0
	v_add_u32_e32 v113, 0x22000, v112
	ds_read_b32 v113, v113
	v_add_u32_e32 v112, 0x21800, v112
	ds_read_b32 v112, v112
	v_add_u32_e32 v114, s4, v198
	v_lshl_add_u32 v114, v114, 2, 0
	v_add_u32_e32 v115, 0x22000, v114
	ds_read_b32 v115, v115
	v_add_u32_e32 v114, 0x21800, v114
	ds_read_b32 v114, v114
	s_and_saveexec_b64 s[70:71], s[46:47]
	s_waitcnt lgkmcnt(7)
	v_sub_f32_e32 v109, v22, v109
	v_mul_f32_e32 v109, 0x3fb8aa3b, v109
	v_exp_f32_e32 v109, v109
	s_nop 0
	v_mul_f32_e32 v109, v10, v109
	s_waitcnt lgkmcnt(6)
	v_mul_f32_e32 v24, v108, v109
	s_or_b64 exec, exec, s[70:71]
	s_and_saveexec_b64 s[70:71], s[48:49]
	s_waitcnt lgkmcnt(5)
	v_sub_f32_e32 v111, v22, v111
	v_mul_f32_e32 v111, 0x3fb8aa3b, v111
	v_exp_f32_e32 v111, v111
	s_nop 0
	v_mul_f32_e32 v111, v11, v111
	s_waitcnt lgkmcnt(4)
	v_mul_f32_e32 v23, v110, v111
	s_or_b64 exec, exec, s[70:71]
	v_mov_b32_e32 v25, 0
	v_mov_b32_e32 v26, 0
	s_and_saveexec_b64 s[70:71], s[50:51]
	s_waitcnt lgkmcnt(3)
	v_sub_f32_e32 v113, v22, v113
	v_mul_f32_e32 v113, 0x3fb8aa3b, v113
	v_exp_f32_e32 v113, v113
	s_nop 0
	v_mul_f32_e32 v113, v12, v113
	s_waitcnt lgkmcnt(2)
	v_mul_f32_e32 v26, v112, v113
	s_or_b64 exec, exec, s[70:71]
	s_and_saveexec_b64 s[70:71], s[52:53]
	s_waitcnt lgkmcnt(1)
	v_sub_f32_e32 v115, v22, v115
	v_mul_f32_e32 v115, 0x3fb8aa3b, v115
	v_exp_f32_e32 v115, v115
	s_nop 0
	v_mul_f32_e32 v115, v13, v115
	s_waitcnt lgkmcnt(0)
	v_mul_f32_e32 v25, v114, v115
	s_or_b64 exec, exec, s[70:71]
	v_cvt_pk_bf16_f32 v24, v24, v23
	v_cvt_pk_bf16_f32 v25, v26, v25
	ds_write_b64 v214, v[24:25] offset:9248
	v_mov_b32_e32 v23, 0
	v_mov_b32_e32 v24, 0
	v_add_u32_e32 v108, s4, v199
	v_lshl_add_u32 v108, v108, 2, 0
	v_add_u32_e32 v109, 0x22000, v108
	ds_read_b32 v109, v109
	v_add_u32_e32 v108, 0x21800, v108
	ds_read_b32 v108, v108
	v_add_u32_e32 v110, s4, v200
	v_lshl_add_u32 v110, v110, 2, 0
	v_add_u32_e32 v111, 0x22000, v110
	ds_read_b32 v111, v111
	v_add_u32_e32 v110, 0x21800, v110
	ds_read_b32 v110, v110
	v_add_u32_e32 v112, s4, v201
	v_lshl_add_u32 v112, v112, 2, 0
	v_add_u32_e32 v113, 0x22000, v112
	ds_read_b32 v113, v113
	v_add_u32_e32 v112, 0x21800, v112
	ds_read_b32 v112, v112
	v_add_u32_e32 v114, s4, v202
	v_lshl_add_u32 v114, v114, 2, 0
	v_add_u32_e32 v115, 0x22000, v114
	ds_read_b32 v115, v115
	v_add_u32_e32 v114, 0x21800, v114
	ds_read_b32 v114, v114
	s_and_saveexec_b64 s[70:71], s[54:55]
	s_waitcnt lgkmcnt(7)
	v_sub_f32_e32 v109, v22, v109
	v_mul_f32_e32 v109, 0x3fb8aa3b, v109
	v_exp_f32_e32 v109, v109
	s_nop 0
	v_mul_f32_e32 v109, v14, v109
	s_waitcnt lgkmcnt(6)
	v_mul_f32_e32 v24, v108, v109
	s_or_b64 exec, exec, s[70:71]
	s_and_saveexec_b64 s[70:71], s[56:57]
	s_waitcnt lgkmcnt(5)
	v_sub_f32_e32 v111, v22, v111
	v_mul_f32_e32 v111, 0x3fb8aa3b, v111
	v_exp_f32_e32 v111, v111
	s_nop 0
	v_mul_f32_e32 v111, v15, v111
	s_waitcnt lgkmcnt(4)
	v_mul_f32_e32 v23, v110, v111
	s_or_b64 exec, exec, s[70:71]
	v_mov_b32_e32 v25, 0
	v_mov_b32_e32 v26, 0
	s_and_saveexec_b64 s[70:71], s[58:59]
	s_waitcnt lgkmcnt(3)
	v_sub_f32_e32 v113, v22, v113
	v_mul_f32_e32 v113, 0x3fb8aa3b, v113
	v_exp_f32_e32 v113, v113
	s_nop 0
	v_mul_f32_e32 v113, v16, v113
	s_waitcnt lgkmcnt(2)
	v_mul_f32_e32 v26, v112, v113
	s_or_b64 exec, exec, s[70:71]
	s_and_saveexec_b64 s[70:71], s[60:61]
	s_waitcnt lgkmcnt(1)
	v_sub_f32_e32 v115, v22, v115
	v_mul_f32_e32 v115, 0x3fb8aa3b, v115
	v_exp_f32_e32 v115, v115
	s_nop 0
	v_mul_f32_e32 v115, v17, v115
	s_waitcnt lgkmcnt(0)
	v_mul_f32_e32 v25, v114, v115
	s_or_b64 exec, exec, s[70:71]
	v_cvt_pk_bf16_f32 v24, v24, v23
	v_cvt_pk_bf16_f32 v25, v26, v25
	ds_write_b64 v214, v[24:25] offset:9280
	v_mov_b32_e32 v23, 0
	v_mov_b32_e32 v24, 0
	v_add_u32_e32 v108, s4, v203
	v_lshl_add_u32 v108, v108, 2, 0
	v_add_u32_e32 v109, 0x22000, v108
	ds_read_b32 v109, v109
	v_add_u32_e32 v108, 0x21800, v108
	ds_read_b32 v108, v108
	v_add_u32_e32 v110, s4, v204
	v_lshl_add_u32 v110, v110, 2, 0
	v_add_u32_e32 v111, 0x22000, v110
	ds_read_b32 v111, v111
	v_add_u32_e32 v110, 0x21800, v110
	ds_read_b32 v110, v110
	v_add_u32_e32 v112, s4, v205
	v_lshl_add_u32 v112, v112, 2, 0
	v_add_u32_e32 v113, 0x22000, v112
	ds_read_b32 v113, v113
	v_add_u32_e32 v112, 0x21800, v112
	ds_read_b32 v112, v112
	v_add_u32_e32 v114, s4, v206
	v_lshl_add_u32 v114, v114, 2, 0
	v_add_u32_e32 v115, 0x22000, v114
	ds_read_b32 v115, v115
	v_add_u32_e32 v114, 0x21800, v114
	ds_read_b32 v114, v114
	s_and_saveexec_b64 s[70:71], s[62:63]
	s_waitcnt lgkmcnt(7)
	v_sub_f32_e32 v109, v22, v109
	v_mul_f32_e32 v109, 0x3fb8aa3b, v109
	v_exp_f32_e32 v109, v109
	s_nop 0
	v_mul_f32_e32 v109, v18, v109
	s_waitcnt lgkmcnt(6)
	v_mul_f32_e32 v24, v108, v109
	s_or_b64 exec, exec, s[70:71]
	s_and_saveexec_b64 s[70:71], s[64:65]
	s_waitcnt lgkmcnt(5)
	v_sub_f32_e32 v111, v22, v111
	v_mul_f32_e32 v111, 0x3fb8aa3b, v111
	v_exp_f32_e32 v111, v111
	s_nop 0
	v_mul_f32_e32 v111, v19, v111
	s_waitcnt lgkmcnt(4)
	v_mul_f32_e32 v23, v110, v111
	s_or_b64 exec, exec, s[70:71]
	v_mov_b32_e32 v25, 0
	v_mov_b32_e32 v26, 0
	s_and_saveexec_b64 s[70:71], s[66:67]
	s_waitcnt lgkmcnt(3)
	v_sub_f32_e32 v113, v22, v113
	v_mul_f32_e32 v113, 0x3fb8aa3b, v113
	v_exp_f32_e32 v113, v113
	s_nop 0
	v_mul_f32_e32 v113, v20, v113
	s_waitcnt lgkmcnt(2)
	v_mul_f32_e32 v26, v112, v113
	s_or_b64 exec, exec, s[70:71]
	s_and_saveexec_b64 s[70:71], s[68:69]
	s_waitcnt lgkmcnt(1)
	v_sub_f32_e32 v115, v22, v115
	v_mul_f32_e32 v115, 0x3fb8aa3b, v115
	v_exp_f32_e32 v115, v115
	s_nop 0
	v_mul_f32_e32 v115, v21, v115
	s_waitcnt lgkmcnt(0)
	v_mul_f32_e32 v25, v114, v115
	s_or_b64 exec, exec, s[70:71]
	s_waitcnt lgkmcnt(3)
	v_cvt_pk_bf16_f32 v22, v24, v23
	v_cvt_pk_bf16_f32 v23, v26, v25
	s_lshl_b32 s4, s34, 7
	v_add_u32_e32 v154, s4, v212
	ds_write_b64 v214, v[22:23] offset:9312
	s_waitcnt lgkmcnt(0)
	s_barrier
	ds_read_b64_tr_b16 v[22:23], v154
	ds_read_b64_tr_b16 v[24:25], v154 offset:4160
	ds_read_b64_tr_b16 v[28:29], v154 offset:4192
	ds_read_b128 v[34:37], v215
	ds_read_b64_tr_b16 v[26:27], v154 offset:32
	ds_read_b64_tr_b16 v[140:141], v154 offset:64
	ds_read_b64_tr_b16 v[216:217], v154 offset:96
	ds_read_b64_tr_b16 v[142:143], v154 offset:4224
	ds_read_b64_tr_b16 v[218:219], v154 offset:4256
	ds_read_b128 v[236:239], v215 offset:2304
	s_waitcnt lgkmcnt(6)
	v_mfma_f32_16x16x32_bf16 v[114:117], v[22:25], v[34:37], 0
	s_andn2_b64 vcc, exec, s[0:1]
	s_waitcnt lgkmcnt(5)
	v_mfma_f32_16x16x32_bf16 v[110:113], v[26:29], v[34:37], 0
	s_waitcnt lgkmcnt(2)
	v_mfma_f32_16x16x32_bf16 v[106:109], v[140:143], v[34:37], 0
	s_waitcnt lgkmcnt(1)
	v_mfma_f32_16x16x32_bf16 v[102:105], v[216:219], v[34:37], 0
	s_waitcnt lgkmcnt(0)
	v_mfma_f32_16x16x32_bf16 v[42:45], v[22:25], v[236:239], 0
	v_mfma_f32_16x16x32_bf16 v[34:37], v[26:29], v[236:239], 0
	v_mfma_f32_16x16x32_bf16 v[26:29], v[140:143], v[236:239], 0
	v_mfma_f32_16x16x32_bf16 v[22:25], v[216:219], v[236:239], 0
	s_cbranch_vccnz .LBB0_601
	ds_read_b64_tr_b16 v[142:143], v154 offset:37440
	ds_read_b64_tr_b16 v[140:141], v154 offset:33280
	ds_read_b64_tr_b16 v[216:217], v154 offset:33312
	ds_read_b64_tr_b16 v[218:219], v154 offset:37472
	ds_read_b64_tr_b16 v[236:237], v154 offset:33344
	ds_read_b64_tr_b16 v[238:239], v154 offset:37504
	ds_read_b64_tr_b16 v[240:241], v154 offset:33376
	ds_read_b64_tr_b16 v[242:243], v154 offset:37536
	ds_read_b128 v[244:247], v215 offset:64
	s_waitcnt lgkmcnt(0)
	v_mfma_f32_16x16x32_bf16 v[114:117], v[140:143], v[244:247], v[114:117]
	v_mfma_f32_16x16x32_bf16 v[110:113], v[216:219], v[244:247], v[110:113]
	v_mfma_f32_16x16x32_bf16 v[106:109], v[236:239], v[244:247], v[106:109]
	v_mfma_f32_16x16x32_bf16 v[102:105], v[240:243], v[244:247], v[102:105]
	ds_read_b128 v[244:247], v215 offset:2368
	s_waitcnt lgkmcnt(0)
	v_mfma_f32_16x16x32_bf16 v[42:45], v[140:143], v[244:247], v[42:45]
	v_mfma_f32_16x16x32_bf16 v[34:37], v[216:219], v[244:247], v[34:37]
	v_mfma_f32_16x16x32_bf16 v[26:29], v[236:239], v[244:247], v[26:29]
	v_mfma_f32_16x16x32_bf16 v[22:25], v[240:243], v[244:247], v[22:25]
